# expert-value loop: 16-bit expert id folded into v_mad_u32_u16 via op_sel (one VALU op fewer per round)
# baseline (speedup 1.0000x reference)
; DI void eseg_load(ESeg& r, __amdgpu_buffer_rsrc_t rs, int voff) { r.a = __builtin_amdgcn_raw_buffer_load_b128(rs, voff, 0, 0); r.b = __builtin_amdgcn_raw_buffer_load_b64(rs, voff + 16, 0, 0); }
; DI int id_of(const u32x4 (&d)[2], int r, unsigned mask = 0xffffu) { const unsigned w = d[r >> 3][(r >> 1) & 3]; return (r & 1) ? (int)((w >> 16) & mask) : (int)(w & mask); }
;     const Frame F = mkframe(wv);
;     int x, wx, nwx; xcd_split(F, x, wx, nwx);
;     const int lane = F.lane, s = lane & 7, g = lane >> 3, s24 = s * 24;
;     const __amdgpu_buffer_rsrc_t VS = __builtin_amdgcn_make_buffer_rsrc((void*)uniform_ptr((unsigned char*)F.V + (size_t)x * ESLICE), 0, (int)ESLICE, 0x00020000);
;     const unsigned short* RI16 = (const unsigned short*)(F.ws + WS_RIDX); const float* Wg = (const float*)(F.ws + WS_PW) + g * 16;
;     const bool b3 = (lane >> 3) & 1; const int col = (((lane >> 5) * 2 + ((lane >> 4) & 1)) * 2 + (b3 ? 1 : 0)) * 256 + (8 * x + s) * 4;
;     int t = wx; if (t >= nrows) return;
;     ESeg rw[16]; u32x4 idn[2], idnn[2]; f32x4 wq[4];
;     { u32x4 idc[2]; ids_load(idc, RI16, t, g);
; #pragma unroll
;       for (int r = 0; r < 16; ++r) eseg_load(rw[r], VS, id_of(idc, r, mask) * ESEG + s24); }
; #pragma unroll
;     for (int q = 0; q < 4; ++q) wq[q] = *(const f32x4*)(Wg + (size_t)t * 128 + q * 4);
;     ids_load(idn, RI16, t + nwx < nrows ? t + nwx : t, g);
;     __builtin_amdgcn_s_waitcnt(0);
.LBB0_1092:
	s_andn2_b64 vcc, exec, s[0:1]
	s_cbranch_vccnz .LBB0_1148
	s_waitcnt vmcnt(0)
	v_mov_b32_e32 v0, v129
	v_readlane_b32 s0, v253, 54
	v_mbcnt_lo_u32_b32 v0, -1, v0
	v_mbcnt_hi_u32_b32 v2, -1, v0
	s_mov_b32 s3, s88
	v_mov_b32_e32 v0, s0
	s_load_dword s2, s[90:91], 0x0
	ds_read_b64 v[0:1], v0
	s_waitcnt lgkmcnt(0)
	v_mov_b32_e32 v0, s79
	ds_read_b64 v[0:1], v0
	v_readlane_b32 s1, v252, 0
	v_readlane_b32 s0, v253, 33
	s_add_i32 s1, s3, s1
	s_add_i32 s0, s3, s0
	s_waitcnt lgkmcnt(0)
	v_readfirstlane_b32 s5, v1
	v_readfirstlane_b32 s4, v0
	s_ashr_i32 s1, s1, 3
	v_and_b32_e64 v0, s2, 7
	v_and_b32_e32 v1, 8, v2
	v_cmp_eq_u32_e32 vcc, 0, v1
	v_mov_b32_e32 v1, s1
	v_mov_b32_e32 v3, s0
	v_cmp_eq_u32_e64 s[0:1], 0, v0
	s_nop 1
	v_cndmask_b32_e64 v0, v1, v3, s[0:1]
	v_mov_b32_e32 v1, s3
	v_mov_b32_e32 v3, s80
	v_cndmask_b32_e64 v1, v1, v3, s[0:1]
	v_and_b32_e32 v3, 7, v1
	v_mul_u32_u24_e32 v128, 0x300000, v3
	v_lshl_add_u64 v[4:5], s[4:5], 0, v[128:129]
	s_mov_b64 s[0:1], 0x8c00000
	v_lshl_add_u64 v[4:5], v[4:5], 0, s[0:1]
	v_cmp_gt_i32_e64 s[0:1], s15, v0
	v_readfirstlane_b32 s3, v5
	v_readfirstlane_b32 s48, v4
	s_and_saveexec_b64 s[6:7], s[0:1]
	s_movk_i32 s12, 0x80
	s_movk_i32 s13, 0x4000
	s_mov_b32 s14, 0x3fb504f3
	s_cbranch_execz .LBB0_1096
	v_lshlrev_b32_e32 v1, 1, v2
	s_and_b32 s49, s3, 0xffff
	v_and_b32_e32 v12, -16, v1
	s_add_u32 s8, s4, 0x42c00000
	v_ashrrev_i32_e32 v1, 31, v0
	v_ashrrev_i32_e32 v13, 31, v12
	s_addc_u32 s9, s5, 0
	v_lshlrev_b64 v[4:5], 8, v[0:1]
	v_lshl_add_u64 v[4:5], s[8:9], 0, v[4:5]
	v_lshlrev_b64 v[14:15], 1, v[12:13]
	v_lshl_add_u64 v[8:9], v[4:5], 0, v[14:15]
	global_load_dwordx4 v[4:7], v[8:9], off
	s_nop 0
	global_load_dwordx4 v[8:11], v[8:9], off offset:16
	v_lshl_add_u64 v[12:13], v[12:13], 2, s[4:5]
	s_mov_b64 s[0:1], 0x3e400000
	v_lshlrev_b64 v[16:17], 9, v[0:1]
	v_lshl_add_u64 v[214:215], v[12:13], 0, s[0:1]
	v_and_b32_e32 v18, 7, v2
	v_lshl_add_u64 v[12:13], v[214:215], 0, v[16:17]
	v_lshlrev_b32_e32 v128, 4, v18
	v_lshlrev_b32_e32 v222, 3, v18
	v_add_u32_e32 v222, 0x200000, v222
	global_load_dwordx4 v[162:165], v[12:13], off offset:48
	global_load_dwordx4 v[174:177], v[12:13], off offset:32
	global_load_dwordx4 v[190:193], v[12:13], off offset:16
	global_load_dwordx4 v[178:181], v[12:13], off
	v_add_u32_e32 v19, s2, v0
	v_cmp_gt_i32_e64 s[0:1], s15, v19
	v_lshlrev_b32_e32 v2, 5, v2
	s_ashr_i32 s3, s2, 31
	v_lshl_add_u64 v[218:219], s[8:9], 0, v[14:15]
	s_mov_b64 s[10:11], 0
	s_waitcnt vmcnt(5)
	v_and_b32_e32 v12, 0xffff, v4
	v_lshrrev_b32_e32 v4, 16, v4
	v_and_b32_e32 v13, 0xffff, v5
	v_lshrrev_b32_e32 v5, 16, v5
	v_and_b32_e32 v16, 0xffff, v6
	v_lshrrev_b32_e32 v6, 16, v6
	v_and_b32_e32 v17, 0xffff, v7
	v_lshrrev_b32_e32 v7, 16, v7
	s_waitcnt vmcnt(4)
	v_and_b32_e32 v20, 0xffff, v8
	v_lshrrev_b32_e32 v8, 16, v8
	v_and_b32_e32 v21, 0xffff, v9
	v_lshrrev_b32_e32 v9, 16, v9
	v_and_b32_e32 v22, 0xffff, v10
	v_lshrrev_b32_e32 v10, 16, v10
	v_and_b32_e32 v23, 0xffff, v11
	v_lshrrev_b32_e32 v11, 16, v11
	v_lshl_add_u32 v211, v12, 6, v222
	v_lshl_add_u32 v12, v12, 7, v128
	buffer_load_dwordx4 v[122:125], v12, s[48:51], 0 offen
	buffer_load_dwordx2 v[126:127], v211, s[48:51], 0 offen
	v_lshl_add_u32 v211, v4, 6, v222
	v_lshl_add_u32 v4, v4, 7, v128
	buffer_load_dwordx4 v[32:35], v4, s[48:51], 0 offen
	buffer_load_dwordx2 v[36:37], v211, s[48:51], 0 offen
	v_lshl_add_u32 v211, v13, 6, v222
	v_lshl_add_u32 v13, v13, 7, v128
	buffer_load_dwordx4 v[116:119], v13, s[48:51], 0 offen
	buffer_load_dwordx2 v[120:121], v211, s[48:51], 0 offen
	v_lshl_add_u32 v211, v5, 6, v222
	v_lshl_add_u32 v5, v5, 7, v128
	buffer_load_dwordx4 v[38:41], v5, s[48:51], 0 offen
	buffer_load_dwordx2 v[42:43], v211, s[48:51], 0 offen
	v_lshl_add_u32 v211, v16, 6, v222
	v_lshl_add_u32 v16, v16, 7, v128
	buffer_load_dwordx4 v[110:113], v16, s[48:51], 0 offen
	buffer_load_dwordx2 v[114:115], v211, s[48:51], 0 offen
	v_lshl_add_u32 v211, v6, 6, v222
	v_lshl_add_u32 v6, v6, 7, v128
	buffer_load_dwordx4 v[44:47], v6, s[48:51], 0 offen
	buffer_load_dwordx2 v[48:49], v211, s[48:51], 0 offen
	v_lshl_add_u32 v211, v17, 6, v222
	v_lshl_add_u32 v17, v17, 7, v128
	buffer_load_dwordx4 v[104:107], v17, s[48:51], 0 offen
	buffer_load_dwordx2 v[108:109], v211, s[48:51], 0 offen
	v_lshl_add_u32 v211, v7, 6, v222
	v_lshl_add_u32 v7, v7, 7, v128
	buffer_load_dwordx4 v[50:53], v7, s[48:51], 0 offen
	buffer_load_dwordx2 v[54:55], v211, s[48:51], 0 offen
	v_lshl_add_u32 v211, v20, 6, v222
	v_lshl_add_u32 v20, v20, 7, v128
	buffer_load_dwordx4 v[98:101], v20, s[48:51], 0 offen
	buffer_load_dwordx2 v[102:103], v211, s[48:51], 0 offen
	v_lshl_add_u32 v211, v8, 6, v222
	v_lshl_add_u32 v8, v8, 7, v128
	buffer_load_dwordx4 v[56:59], v8, s[48:51], 0 offen
	buffer_load_dwordx2 v[60:61], v211, s[48:51], 0 offen
	v_lshl_add_u32 v211, v21, 6, v222
	v_lshl_add_u32 v21, v21, 7, v128
	buffer_load_dwordx4 v[92:95], v21, s[48:51], 0 offen
	buffer_load_dwordx2 v[96:97], v211, s[48:51], 0 offen
	v_lshl_add_u32 v211, v9, 6, v222
	v_lshl_add_u32 v9, v9, 7, v128
	buffer_load_dwordx4 v[62:65], v9, s[48:51], 0 offen
	buffer_load_dwordx2 v[66:67], v211, s[48:51], 0 offen
	v_lshl_add_u32 v211, v22, 6, v222
	v_lshl_add_u32 v22, v22, 7, v128
	buffer_load_dwordx4 v[86:89], v22, s[48:51], 0 offen
	buffer_load_dwordx2 v[90:91], v211, s[48:51], 0 offen
	v_lshl_add_u32 v211, v10, 6, v222
	v_lshl_add_u32 v10, v10, 7, v128
	buffer_load_dwordx4 v[68:71], v10, s[48:51], 0 offen
	buffer_load_dwordx2 v[72:73], v211, s[48:51], 0 offen
	v_lshl_add_u32 v211, v23, 6, v222
	v_lshl_add_u32 v23, v23, 7, v128
	buffer_load_dwordx4 v[80:83], v23, s[48:51], 0 offen
	buffer_load_dwordx2 v[84:85], v211, s[48:51], 0 offen
	v_lshl_add_u32 v211, v11, 6, v222
	v_lshl_add_u32 v11, v11, 7, v128
	buffer_load_dwordx4 v[74:77], v11, s[48:51], 0 offen
	buffer_load_dwordx2 v[78:79], v211, s[48:51], 0 offen
	v_cndmask_b32_e64 v4, v0, v19, s[0:1]
	v_ashrrev_i32_e32 v5, 31, v4
	v_lshlrev_b64 v[4:5], 8, v[4:5]
	v_lshl_add_u64 v[4:5], s[8:9], 0, v[4:5]
	v_lshl_add_u64 v[4:5], v[4:5], 0, v[14:15]
	global_load_dwordx4 v[158:161], v[4:5], off offset:16
	global_load_dwordx4 v[186:189], v[4:5], off
	v_lshlrev_b32_e32 v4, 5, v3
	v_lshlrev_b32_e32 v5, 2, v18
	v_and_b32_e32 v6, 0xffffff00, v2
	v_or3_b32 v216, v4, v5, v6
	v_or3_b32 v4, v6, v4, v5
	v_lshlrev_b64 v[2:3], 13, v[0:1]
	v_ashrrev_i32_e32 v5, 31, v4
	v_lshl_add_u64 v[2:3], v[4:5], 2, v[2:3]
	v_lshl_add_u64 v[2:3], s[4:5], 0, v[2:3]
	s_mov_b64 s[0:1], 0xcc00000
	v_ashrrev_i32_e32 v217, 31, v216
	v_lshl_add_u64 v[220:221], v[2:3], 0, s[0:1]
	s_lshl_b64 s[8:9], s[2:3], 13
	s_lshl_b32 s3, s2, 1
	s_waitcnt vmcnt(0) expcnt(0) lgkmcnt(0)
; DI void eseg_load(ESeg& r, __amdgpu_buffer_rsrc_t rs, int voff) { r.a = __builtin_amdgcn_raw_buffer_load_b128(rs, voff, 0, 0); r.b = __builtin_amdgcn_raw_buffer_load_b64(rs, voff + 16, 0, 0); }
; DI v32f eseg_unpack(const ESeg& r) { return __builtin_amdgcn_cvt_scalef32_pk32_f32_fp6((v6i){(int)r.a.x, (int)r.a.y, (int)r.a.z, (int)r.a.w, (int)r.b.x, (int)r.b.y}, 1.0f); }
; DI int id_of(const u32x4 (&d)[2], int r, unsigned mask = 0xffffu) { const unsigned w = d[r >> 3][(r >> 1) & 3]; return (r & 1) ? (int)((w >> 16) & mask) : (int)(w & mask); }
;     ...
;     for (;;) {
;         const int tn = t + nwx, tnn = tn + nwx, tn_c = tn < nrows ? tn : t, tnn_c = tnn < nrows ? tnn : t;
;         ids_load(idnn, RI16, tnn_c, g);
;         float wt[16];
; #pragma unroll
;         for (int q = 0; q < 4; ++q) { wt[q * 4] = wq[q].x; wt[q * 4 + 1] = wq[q].y; wt[q * 4 + 2] = wq[q].z; wt[q * 4 + 3] = wq[q].w; }
; #pragma unroll
;         for (int q = 0; q < 16; ++q) asm volatile("" : "+v"(wt[q]));
;         __builtin_amdgcn_sched_barrier(0);
; #pragma unroll
;         for (int q = 0; q < 4; ++q) wq[q] = *(const f32x4*)(Wg + (size_t)tn_c * 128 + q * 4);
;         float* xp = F.X + (size_t)t * D + col;
;         const f32x4 x1 = *(const f32x4*)xp, g2 = *(const f32x4*)(F.mod + ((size_t)l * 9 + modrow(t)) * MODW + 5 * D + col);
;         __builtin_amdgcn_sched_barrier(0);
;         f32x2 fa[16];
; #pragma unroll
;         for (int j = 0; j < 16; ++j) fa[j] = (f32x2){0.f, 0.f};
; #pragma unroll
;         for (int r = 0; r < 16; ++r) {
;             const v32f rr = eseg_unpack(rw[r]); const f32x2 w2 = {wt[r], wt[r]};
; #pragma unroll
;             for (int j = 0; j < 16; ++j) fa[j] = __builtin_elementwise_fma((f32x2){rr[2 * j], rr[2 * j + 1]}, w2, fa[j]);
;             eseg_load(rw[r], VS, id_of(idn, r, mask) * ESEG + s24);
;             if (r & 1) __builtin_amdgcn_sched_barrier(0);
.LBB0_1095:
	v_add_u32_e32 v1, s3, v0
	v_cmp_gt_i32_e64 s[0:1], s15, v1
	v_add_u32_e32 v250, s2, v0
	v_cmp_le_i32_e64 s[36:37], s15, v250
	v_cndmask_b32_e64 v2, v0, v1, s[0:1]
	v_ashrrev_i32_e32 v3, 31, v2
	v_lshlrev_b64 v[2:3], 8, v[2:3]
	v_lshl_add_u64 v[2:3], v[218:219], 0, v[2:3]
	global_load_dwordx4 v[130:133], v[2:3], off offset:16
	global_load_dwordx4 v[134:137], v[2:3], off
	v_cmp_gt_i32_e64 s[0:1], s15, v250
	s_nop 1
	v_cndmask_b32_e64 v2, v0, v250, s[0:1]
	v_ashrrev_i32_e32 v1, 31, v0
	v_lshrrev_b32_e32 v1, 21, v1
	v_add_u32_e32 v1, v0, v1
	v_ashrrev_i32_e32 v1, 11, v1
	v_cmp_gt_i32_e64 s[0:1], s13, v0
	v_ashrrev_i32_e32 v3, 31, v2
	v_lshlrev_b64 v[2:3], 9, v[2:3]
	v_cndmask_b32_e64 v0, 8, v1, s[0:1]
	s_mul_i32 s0, s92, 9
	v_add_u32_e32 v0, s0, v0
	v_lshl_add_u64 v[2:3], v[214:215], 0, v[2:3]
	v_mul_hi_i32_i24_e32 v1, 0xc000, v0
	v_mul_i32_i24_e32 v0, 0xc000, v0
	global_load_dwordx4 v[138:141], v[2:3], off offset:48
	global_load_dwordx4 v[142:145], v[2:3], off offset:32
	global_load_dwordx4 v[146:149], v[2:3], off offset:16
	global_load_dwordx4 v[150:153], v[2:3], off
	global_load_dwordx4 v[166:169], v[220:221], off
	v_lshl_add_u64 v[0:1], s[4:5], 0, v[0:1]
	v_lshl_add_u64 v[0:1], v[216:217], 2, v[0:1]
	s_mov_b32 s0, 0x10a000
	v_add_co_u32_e64 v0, s[0:1], s0, v0
	s_nop 1
	v_addc_co_u32_e64 v1, s[0:1], 0, v1, s[0:1]
	global_load_dwordx4 v[170:173], v[0:1], off
	s_waitcnt vmcnt(39)
	v_cvt_scalef32_pk32_f32_fp6 v[0:31], v[122:127], 1.0
	v_mad_u32_u16 v211, v186, 64, v222 op_sel:[0,0,0,0]
	v_mad_u32_u16 v210, v186, s12, v128 op_sel:[0,0,0,0]
	v_pk_fma_f32 v[194:195], v[0:1], v[178:179], 0 op_sel_hi:[1,0,0]
	v_pk_fma_f32 v[196:197], v[2:3], v[178:179], 0 op_sel_hi:[1,0,0]
	v_pk_fma_f32 v[198:199], v[4:5], v[178:179], 0 op_sel_hi:[1,0,0]
	v_pk_fma_f32 v[200:201], v[6:7], v[178:179], 0 op_sel_hi:[1,0,0]
	v_pk_fma_f32 v[202:203], v[8:9], v[178:179], 0 op_sel_hi:[1,0,0]
	v_pk_fma_f32 v[204:205], v[10:11], v[178:179], 0 op_sel_hi:[1,0,0]
	v_pk_fma_f32 v[224:225], v[12:13], v[178:179], 0 op_sel_hi:[1,0,0]
	v_pk_fma_f32 v[226:227], v[14:15], v[178:179], 0 op_sel_hi:[1,0,0]
	v_pk_fma_f32 v[228:229], v[16:17], v[178:179], 0 op_sel_hi:[1,0,0]
	v_pk_fma_f32 v[230:231], v[18:19], v[178:179], 0 op_sel_hi:[1,0,0]
	v_pk_fma_f32 v[232:233], v[20:21], v[178:179], 0 op_sel_hi:[1,0,0]
	v_pk_fma_f32 v[234:235], v[22:23], v[178:179], 0 op_sel_hi:[1,0,0]
	v_pk_fma_f32 v[236:237], v[24:25], v[178:179], 0 op_sel_hi:[1,0,0]
	v_pk_fma_f32 v[182:183], v[26:27], v[178:179], 0 op_sel_hi:[1,0,0]
	v_pk_fma_f32 v[184:185], v[28:29], v[178:179], 0 op_sel_hi:[1,0,0]
	v_pk_fma_f32 v[208:209], v[30:31], v[178:179], 0 op_sel_hi:[1,0,0]
	buffer_load_dwordx4 v[122:125], v210, s[48:51], 0 offen
	buffer_load_dwordx2 v[126:127], v211, s[48:51], 0 offen
	s_waitcnt vmcnt(39)
	v_cvt_scalef32_pk32_f32_fp6 v[0:31], v[32:37], 1.0
	v_mad_u32_u16 v211, v186, 64, v222 op_sel:[1,0,0,0]
	v_mad_u32_u16 v210, v186, s12, v128 op_sel:[1,0,0,0]
	v_pk_fma_f32 v[194:195], v[0:1], v[178:179], v[194:195] op_sel:[0,1,0] op_sel_hi:[1,1,1]
	v_pk_fma_f32 v[196:197], v[2:3], v[178:179], v[196:197] op_sel:[0,1,0] op_sel_hi:[1,1,1]
	v_pk_fma_f32 v[198:199], v[4:5], v[178:179], v[198:199] op_sel:[0,1,0] op_sel_hi:[1,1,1]
	v_pk_fma_f32 v[200:201], v[6:7], v[178:179], v[200:201] op_sel:[0,1,0] op_sel_hi:[1,1,1]
	v_pk_fma_f32 v[202:203], v[8:9], v[178:179], v[202:203] op_sel:[0,1,0] op_sel_hi:[1,1,1]
	v_pk_fma_f32 v[204:205], v[10:11], v[178:179], v[204:205] op_sel:[0,1,0] op_sel_hi:[1,1,1]
	v_pk_fma_f32 v[224:225], v[12:13], v[178:179], v[224:225] op_sel:[0,1,0] op_sel_hi:[1,1,1]
	v_pk_fma_f32 v[226:227], v[14:15], v[178:179], v[226:227] op_sel:[0,1,0] op_sel_hi:[1,1,1]
	v_pk_fma_f32 v[228:229], v[16:17], v[178:179], v[228:229] op_sel:[0,1,0] op_sel_hi:[1,1,1]
	v_pk_fma_f32 v[230:231], v[18:19], v[178:179], v[230:231] op_sel:[0,1,0] op_sel_hi:[1,1,1]
	v_pk_fma_f32 v[232:233], v[20:21], v[178:179], v[232:233] op_sel:[0,1,0] op_sel_hi:[1,1,1]
	v_pk_fma_f32 v[234:235], v[22:23], v[178:179], v[234:235] op_sel:[0,1,0] op_sel_hi:[1,1,1]
	v_pk_fma_f32 v[236:237], v[24:25], v[178:179], v[236:237] op_sel:[0,1,0] op_sel_hi:[1,1,1]
	v_pk_fma_f32 v[182:183], v[26:27], v[178:179], v[182:183] op_sel:[0,1,0] op_sel_hi:[1,1,1]
	v_pk_fma_f32 v[184:185], v[28:29], v[178:179], v[184:185] op_sel:[0,1,0] op_sel_hi:[1,1,1]
	v_pk_fma_f32 v[208:209], v[30:31], v[178:179], v[208:209] op_sel:[0,1,0] op_sel_hi:[1,1,1]
	buffer_load_dwordx4 v[32:35], v210, s[48:51], 0 offen
	buffer_load_dwordx2 v[36:37], v211, s[48:51], 0 offen
	s_waitcnt vmcnt(39)
	v_cvt_scalef32_pk32_f32_fp6 v[0:31], v[116:121], 1.0
	v_mad_u32_u16 v211, v187, 64, v222 op_sel:[0,0,0,0]
	v_mad_u32_u16 v210, v187, s12, v128 op_sel:[0,0,0,0]
	v_pk_fma_f32 v[194:195], v[0:1], v[180:181], v[194:195] op_sel_hi:[1,0,1]
	v_pk_fma_f32 v[196:197], v[2:3], v[180:181], v[196:197] op_sel_hi:[1,0,1]
	v_pk_fma_f32 v[198:199], v[4:5], v[180:181], v[198:199] op_sel_hi:[1,0,1]
	v_pk_fma_f32 v[200:201], v[6:7], v[180:181], v[200:201] op_sel_hi:[1,0,1]
	v_pk_fma_f32 v[202:203], v[8:9], v[180:181], v[202:203] op_sel_hi:[1,0,1]
	v_pk_fma_f32 v[204:205], v[10:11], v[180:181], v[204:205] op_sel_hi:[1,0,1]
	v_pk_fma_f32 v[224:225], v[12:13], v[180:181], v[224:225] op_sel_hi:[1,0,1]
	v_pk_fma_f32 v[226:227], v[14:15], v[180:181], v[226:227] op_sel_hi:[1,0,1]
	v_pk_fma_f32 v[228:229], v[16:17], v[180:181], v[228:229] op_sel_hi:[1,0,1]
	v_pk_fma_f32 v[230:231], v[18:19], v[180:181], v[230:231] op_sel_hi:[1,0,1]
	v_pk_fma_f32 v[232:233], v[20:21], v[180:181], v[232:233] op_sel_hi:[1,0,1]
	v_pk_fma_f32 v[234:235], v[22:23], v[180:181], v[234:235] op_sel_hi:[1,0,1]
	v_pk_fma_f32 v[236:237], v[24:25], v[180:181], v[236:237] op_sel_hi:[1,0,1]
	v_pk_fma_f32 v[182:183], v[26:27], v[180:181], v[182:183] op_sel_hi:[1,0,1]
	v_pk_fma_f32 v[184:185], v[28:29], v[180:181], v[184:185] op_sel_hi:[1,0,1]
	v_pk_fma_f32 v[208:209], v[30:31], v[180:181], v[208:209] op_sel_hi:[1,0,1]
	buffer_load_dwordx4 v[116:119], v210, s[48:51], 0 offen
	buffer_load_dwordx2 v[120:121], v211, s[48:51], 0 offen
	s_waitcnt vmcnt(39)
; DI void eseg_load(ESeg& r, __amdgpu_buffer_rsrc_t rs, int voff) { r.a = __builtin_amdgcn_raw_buffer_load_b128(rs, voff, 0, 0); r.b = __builtin_amdgcn_raw_buffer_load_b64(rs, voff + 16, 0, 0); }
; DI v32f eseg_unpack(const ESeg& r) { return __builtin_amdgcn_cvt_scalef32_pk32_f32_fp6((v6i){(int)r.a.x, (int)r.a.y, (int)r.a.z, (int)r.a.w, (int)r.b.x, (int)r.b.y}, 1.0f); }
; DI int id_of(const u32x4 (&d)[2], int r, unsigned mask = 0xffffu) { const unsigned w = d[r >> 3][(r >> 1) & 3]; return (r & 1) ? (int)((w >> 16) & mask) : (int)(w & mask); }
;     ...
; #pragma unroll
;         for (int r = 0; r < 16; ++r) {
;             const v32f rr = eseg_unpack(rw[r]); const f32x2 w2 = {wt[r], wt[r]};
; #pragma unroll
;             for (int j = 0; j < 16; ++j) fa[j] = __builtin_elementwise_fma((f32x2){rr[2 * j], rr[2 * j + 1]}, w2, fa[j]);
;             eseg_load(rw[r], VS, id_of(idn, r, mask) * ESEG + s24);
;             if (r & 1) __builtin_amdgcn_sched_barrier(0);
;         }
	v_cvt_scalef32_pk32_f32_fp6 v[0:31], v[38:43], 1.0
	v_mad_u32_u16 v211, v187, 64, v222 op_sel:[1,0,0,0]
	v_mad_u32_u16 v210, v187, s12, v128 op_sel:[1,0,0,0]
	v_pk_fma_f32 v[194:195], v[0:1], v[180:181], v[194:195] op_sel:[0,1,0] op_sel_hi:[1,1,1]
	v_pk_fma_f32 v[196:197], v[2:3], v[180:181], v[196:197] op_sel:[0,1,0] op_sel_hi:[1,1,1]
	v_pk_fma_f32 v[198:199], v[4:5], v[180:181], v[198:199] op_sel:[0,1,0] op_sel_hi:[1,1,1]
	v_pk_fma_f32 v[200:201], v[6:7], v[180:181], v[200:201] op_sel:[0,1,0] op_sel_hi:[1,1,1]
	v_pk_fma_f32 v[202:203], v[8:9], v[180:181], v[202:203] op_sel:[0,1,0] op_sel_hi:[1,1,1]
	v_pk_fma_f32 v[204:205], v[10:11], v[180:181], v[204:205] op_sel:[0,1,0] op_sel_hi:[1,1,1]
	v_pk_fma_f32 v[224:225], v[12:13], v[180:181], v[224:225] op_sel:[0,1,0] op_sel_hi:[1,1,1]
	v_pk_fma_f32 v[226:227], v[14:15], v[180:181], v[226:227] op_sel:[0,1,0] op_sel_hi:[1,1,1]
	v_pk_fma_f32 v[228:229], v[16:17], v[180:181], v[228:229] op_sel:[0,1,0] op_sel_hi:[1,1,1]
	v_pk_fma_f32 v[230:231], v[18:19], v[180:181], v[230:231] op_sel:[0,1,0] op_sel_hi:[1,1,1]
	v_pk_fma_f32 v[232:233], v[20:21], v[180:181], v[232:233] op_sel:[0,1,0] op_sel_hi:[1,1,1]
	v_pk_fma_f32 v[234:235], v[22:23], v[180:181], v[234:235] op_sel:[0,1,0] op_sel_hi:[1,1,1]
	v_pk_fma_f32 v[236:237], v[24:25], v[180:181], v[236:237] op_sel:[0,1,0] op_sel_hi:[1,1,1]
	v_pk_fma_f32 v[182:183], v[26:27], v[180:181], v[182:183] op_sel:[0,1,0] op_sel_hi:[1,1,1]
	v_pk_fma_f32 v[184:185], v[28:29], v[180:181], v[184:185] op_sel:[0,1,0] op_sel_hi:[1,1,1]
	v_pk_fma_f32 v[208:209], v[30:31], v[180:181], v[208:209] op_sel:[0,1,0] op_sel_hi:[1,1,1]
	buffer_load_dwordx4 v[38:41], v210, s[48:51], 0 offen
	buffer_load_dwordx2 v[42:43], v211, s[48:51], 0 offen
	s_waitcnt vmcnt(39)
	v_cvt_scalef32_pk32_f32_fp6 v[0:31], v[110:115], 1.0
	v_mad_u32_u16 v211, v188, 64, v222 op_sel:[0,0,0,0]
	v_mad_u32_u16 v210, v188, s12, v128 op_sel:[0,0,0,0]
	v_pk_fma_f32 v[194:195], v[0:1], v[190:191], v[194:195] op_sel_hi:[1,0,1]
	v_pk_fma_f32 v[196:197], v[2:3], v[190:191], v[196:197] op_sel_hi:[1,0,1]
	v_pk_fma_f32 v[198:199], v[4:5], v[190:191], v[198:199] op_sel_hi:[1,0,1]
	v_pk_fma_f32 v[200:201], v[6:7], v[190:191], v[200:201] op_sel_hi:[1,0,1]
	v_pk_fma_f32 v[202:203], v[8:9], v[190:191], v[202:203] op_sel_hi:[1,0,1]
	v_pk_fma_f32 v[204:205], v[10:11], v[190:191], v[204:205] op_sel_hi:[1,0,1]
	v_pk_fma_f32 v[224:225], v[12:13], v[190:191], v[224:225] op_sel_hi:[1,0,1]
	v_pk_fma_f32 v[226:227], v[14:15], v[190:191], v[226:227] op_sel_hi:[1,0,1]
	v_pk_fma_f32 v[228:229], v[16:17], v[190:191], v[228:229] op_sel_hi:[1,0,1]
	v_pk_fma_f32 v[230:231], v[18:19], v[190:191], v[230:231] op_sel_hi:[1,0,1]
	v_pk_fma_f32 v[232:233], v[20:21], v[190:191], v[232:233] op_sel_hi:[1,0,1]
	v_pk_fma_f32 v[234:235], v[22:23], v[190:191], v[234:235] op_sel_hi:[1,0,1]
	v_pk_fma_f32 v[236:237], v[24:25], v[190:191], v[236:237] op_sel_hi:[1,0,1]
	v_pk_fma_f32 v[182:183], v[26:27], v[190:191], v[182:183] op_sel_hi:[1,0,1]
	v_pk_fma_f32 v[184:185], v[28:29], v[190:191], v[184:185] op_sel_hi:[1,0,1]
	v_pk_fma_f32 v[208:209], v[30:31], v[190:191], v[208:209] op_sel_hi:[1,0,1]
	buffer_load_dwordx4 v[110:113], v210, s[48:51], 0 offen
	buffer_load_dwordx2 v[114:115], v211, s[48:51], 0 offen
	s_waitcnt vmcnt(39)
	v_cvt_scalef32_pk32_f32_fp6 v[0:31], v[44:49], 1.0
	v_mad_u32_u16 v211, v188, 64, v222 op_sel:[1,0,0,0]
	v_mad_u32_u16 v210, v188, s12, v128 op_sel:[1,0,0,0]
	v_pk_fma_f32 v[194:195], v[0:1], v[190:191], v[194:195] op_sel:[0,1,0] op_sel_hi:[1,1,1]
	v_pk_fma_f32 v[196:197], v[2:3], v[190:191], v[196:197] op_sel:[0,1,0] op_sel_hi:[1,1,1]
	v_pk_fma_f32 v[198:199], v[4:5], v[190:191], v[198:199] op_sel:[0,1,0] op_sel_hi:[1,1,1]
	v_pk_fma_f32 v[200:201], v[6:7], v[190:191], v[200:201] op_sel:[0,1,0] op_sel_hi:[1,1,1]
	v_pk_fma_f32 v[202:203], v[8:9], v[190:191], v[202:203] op_sel:[0,1,0] op_sel_hi:[1,1,1]
	v_pk_fma_f32 v[204:205], v[10:11], v[190:191], v[204:205] op_sel:[0,1,0] op_sel_hi:[1,1,1]
	v_pk_fma_f32 v[224:225], v[12:13], v[190:191], v[224:225] op_sel:[0,1,0] op_sel_hi:[1,1,1]
	v_pk_fma_f32 v[226:227], v[14:15], v[190:191], v[226:227] op_sel:[0,1,0] op_sel_hi:[1,1,1]
	v_pk_fma_f32 v[228:229], v[16:17], v[190:191], v[228:229] op_sel:[0,1,0] op_sel_hi:[1,1,1]
	v_pk_fma_f32 v[230:231], v[18:19], v[190:191], v[230:231] op_sel:[0,1,0] op_sel_hi:[1,1,1]
	v_pk_fma_f32 v[232:233], v[20:21], v[190:191], v[232:233] op_sel:[0,1,0] op_sel_hi:[1,1,1]
	v_pk_fma_f32 v[234:235], v[22:23], v[190:191], v[234:235] op_sel:[0,1,0] op_sel_hi:[1,1,1]
	v_pk_fma_f32 v[236:237], v[24:25], v[190:191], v[236:237] op_sel:[0,1,0] op_sel_hi:[1,1,1]
	v_pk_fma_f32 v[182:183], v[26:27], v[190:191], v[182:183] op_sel:[0,1,0] op_sel_hi:[1,1,1]
	v_pk_fma_f32 v[184:185], v[28:29], v[190:191], v[184:185] op_sel:[0,1,0] op_sel_hi:[1,1,1]
	v_pk_fma_f32 v[208:209], v[30:31], v[190:191], v[208:209] op_sel:[0,1,0] op_sel_hi:[1,1,1]
	buffer_load_dwordx4 v[44:47], v210, s[48:51], 0 offen
	buffer_load_dwordx2 v[48:49], v211, s[48:51], 0 offen
	s_waitcnt vmcnt(39)
; DI void eseg_load(ESeg& r, __amdgpu_buffer_rsrc_t rs, int voff) { r.a = __builtin_amdgcn_raw_buffer_load_b128(rs, voff, 0, 0); r.b = __builtin_amdgcn_raw_buffer_load_b64(rs, voff + 16, 0, 0); }
; DI v32f eseg_unpack(const ESeg& r) { return __builtin_amdgcn_cvt_scalef32_pk32_f32_fp6((v6i){(int)r.a.x, (int)r.a.y, (int)r.a.z, (int)r.a.w, (int)r.b.x, (int)r.b.y}, 1.0f); }
; DI int id_of(const u32x4 (&d)[2], int r, unsigned mask = 0xffffu) { const unsigned w = d[r >> 3][(r >> 1) & 3]; return (r & 1) ? (int)((w >> 16) & mask) : (int)(w & mask); }
;     ...
; #pragma unroll
;         for (int r = 0; r < 16; ++r) {
;             const v32f rr = eseg_unpack(rw[r]); const f32x2 w2 = {wt[r], wt[r]};
; #pragma unroll
;             for (int j = 0; j < 16; ++j) fa[j] = __builtin_elementwise_fma((f32x2){rr[2 * j], rr[2 * j + 1]}, w2, fa[j]);
;             eseg_load(rw[r], VS, id_of(idn, r, mask) * ESEG + s24);
;             if (r & 1) __builtin_amdgcn_sched_barrier(0);
;         }
	v_cvt_scalef32_pk32_f32_fp6 v[0:31], v[104:109], 1.0
	v_mad_u32_u16 v211, v189, 64, v222 op_sel:[0,0,0,0]
	v_mad_u32_u16 v210, v189, s12, v128 op_sel:[0,0,0,0]
	v_pk_fma_f32 v[194:195], v[0:1], v[192:193], v[194:195] op_sel_hi:[1,0,1]
	v_pk_fma_f32 v[196:197], v[2:3], v[192:193], v[196:197] op_sel_hi:[1,0,1]
	v_pk_fma_f32 v[198:199], v[4:5], v[192:193], v[198:199] op_sel_hi:[1,0,1]
	v_pk_fma_f32 v[200:201], v[6:7], v[192:193], v[200:201] op_sel_hi:[1,0,1]
	v_pk_fma_f32 v[202:203], v[8:9], v[192:193], v[202:203] op_sel_hi:[1,0,1]
	v_pk_fma_f32 v[204:205], v[10:11], v[192:193], v[204:205] op_sel_hi:[1,0,1]
	v_pk_fma_f32 v[224:225], v[12:13], v[192:193], v[224:225] op_sel_hi:[1,0,1]
	v_pk_fma_f32 v[226:227], v[14:15], v[192:193], v[226:227] op_sel_hi:[1,0,1]
	v_pk_fma_f32 v[228:229], v[16:17], v[192:193], v[228:229] op_sel_hi:[1,0,1]
	v_pk_fma_f32 v[230:231], v[18:19], v[192:193], v[230:231] op_sel_hi:[1,0,1]
	v_pk_fma_f32 v[232:233], v[20:21], v[192:193], v[232:233] op_sel_hi:[1,0,1]
	v_pk_fma_f32 v[234:235], v[22:23], v[192:193], v[234:235] op_sel_hi:[1,0,1]
	v_pk_fma_f32 v[236:237], v[24:25], v[192:193], v[236:237] op_sel_hi:[1,0,1]
	v_pk_fma_f32 v[182:183], v[26:27], v[192:193], v[182:183] op_sel_hi:[1,0,1]
	v_pk_fma_f32 v[184:185], v[28:29], v[192:193], v[184:185] op_sel_hi:[1,0,1]
	v_pk_fma_f32 v[208:209], v[30:31], v[192:193], v[208:209] op_sel_hi:[1,0,1]
	buffer_load_dwordx4 v[104:107], v210, s[48:51], 0 offen
	buffer_load_dwordx2 v[108:109], v211, s[48:51], 0 offen
	s_waitcnt vmcnt(39)
	v_cvt_scalef32_pk32_f32_fp6 v[0:31], v[50:55], 1.0
	v_mad_u32_u16 v211, v189, 64, v222 op_sel:[1,0,0,0]
	v_mad_u32_u16 v210, v189, s12, v128 op_sel:[1,0,0,0]
	v_pk_fma_f32 v[194:195], v[0:1], v[192:193], v[194:195] op_sel:[0,1,0] op_sel_hi:[1,1,1]
	v_pk_fma_f32 v[196:197], v[2:3], v[192:193], v[196:197] op_sel:[0,1,0] op_sel_hi:[1,1,1]
	v_pk_fma_f32 v[198:199], v[4:5], v[192:193], v[198:199] op_sel:[0,1,0] op_sel_hi:[1,1,1]
	v_pk_fma_f32 v[200:201], v[6:7], v[192:193], v[200:201] op_sel:[0,1,0] op_sel_hi:[1,1,1]
	v_pk_fma_f32 v[202:203], v[8:9], v[192:193], v[202:203] op_sel:[0,1,0] op_sel_hi:[1,1,1]
	v_pk_fma_f32 v[204:205], v[10:11], v[192:193], v[204:205] op_sel:[0,1,0] op_sel_hi:[1,1,1]
	v_pk_fma_f32 v[224:225], v[12:13], v[192:193], v[224:225] op_sel:[0,1,0] op_sel_hi:[1,1,1]
	v_pk_fma_f32 v[226:227], v[14:15], v[192:193], v[226:227] op_sel:[0,1,0] op_sel_hi:[1,1,1]
	v_pk_fma_f32 v[228:229], v[16:17], v[192:193], v[228:229] op_sel:[0,1,0] op_sel_hi:[1,1,1]
	v_pk_fma_f32 v[230:231], v[18:19], v[192:193], v[230:231] op_sel:[0,1,0] op_sel_hi:[1,1,1]
	v_pk_fma_f32 v[232:233], v[20:21], v[192:193], v[232:233] op_sel:[0,1,0] op_sel_hi:[1,1,1]
	v_pk_fma_f32 v[234:235], v[22:23], v[192:193], v[234:235] op_sel:[0,1,0] op_sel_hi:[1,1,1]
	v_pk_fma_f32 v[236:237], v[24:25], v[192:193], v[236:237] op_sel:[0,1,0] op_sel_hi:[1,1,1]
	v_pk_fma_f32 v[182:183], v[26:27], v[192:193], v[182:183] op_sel:[0,1,0] op_sel_hi:[1,1,1]
	v_pk_fma_f32 v[184:185], v[28:29], v[192:193], v[184:185] op_sel:[0,1,0] op_sel_hi:[1,1,1]
	v_pk_fma_f32 v[208:209], v[30:31], v[192:193], v[208:209] op_sel:[0,1,0] op_sel_hi:[1,1,1]
	buffer_load_dwordx4 v[50:53], v210, s[48:51], 0 offen
	buffer_load_dwordx2 v[54:55], v211, s[48:51], 0 offen
	s_waitcnt vmcnt(39)
	v_cvt_scalef32_pk32_f32_fp6 v[0:31], v[98:103], 1.0
	v_mad_u32_u16 v211, v158, 64, v222 op_sel:[0,0,0,0]
	v_mad_u32_u16 v210, v158, s12, v128 op_sel:[0,0,0,0]
	v_pk_fma_f32 v[194:195], v[0:1], v[174:175], v[194:195] op_sel_hi:[1,0,1]
	v_pk_fma_f32 v[196:197], v[2:3], v[174:175], v[196:197] op_sel_hi:[1,0,1]
	v_pk_fma_f32 v[198:199], v[4:5], v[174:175], v[198:199] op_sel_hi:[1,0,1]
	v_pk_fma_f32 v[200:201], v[6:7], v[174:175], v[200:201] op_sel_hi:[1,0,1]
	v_pk_fma_f32 v[202:203], v[8:9], v[174:175], v[202:203] op_sel_hi:[1,0,1]
	v_pk_fma_f32 v[204:205], v[10:11], v[174:175], v[204:205] op_sel_hi:[1,0,1]
	v_pk_fma_f32 v[224:225], v[12:13], v[174:175], v[224:225] op_sel_hi:[1,0,1]
	v_pk_fma_f32 v[226:227], v[14:15], v[174:175], v[226:227] op_sel_hi:[1,0,1]
	v_pk_fma_f32 v[228:229], v[16:17], v[174:175], v[228:229] op_sel_hi:[1,0,1]
	v_pk_fma_f32 v[230:231], v[18:19], v[174:175], v[230:231] op_sel_hi:[1,0,1]
	v_pk_fma_f32 v[232:233], v[20:21], v[174:175], v[232:233] op_sel_hi:[1,0,1]
	v_pk_fma_f32 v[234:235], v[22:23], v[174:175], v[234:235] op_sel_hi:[1,0,1]
	v_pk_fma_f32 v[236:237], v[24:25], v[174:175], v[236:237] op_sel_hi:[1,0,1]
	v_pk_fma_f32 v[182:183], v[26:27], v[174:175], v[182:183] op_sel_hi:[1,0,1]
	v_pk_fma_f32 v[184:185], v[28:29], v[174:175], v[184:185] op_sel_hi:[1,0,1]
	v_pk_fma_f32 v[208:209], v[30:31], v[174:175], v[208:209] op_sel_hi:[1,0,1]
	buffer_load_dwordx4 v[98:101], v210, s[48:51], 0 offen
	buffer_load_dwordx2 v[102:103], v211, s[48:51], 0 offen
	s_waitcnt vmcnt(39)
; DI void eseg_load(ESeg& r, __amdgpu_buffer_rsrc_t rs, int voff) { r.a = __builtin_amdgcn_raw_buffer_load_b128(rs, voff, 0, 0); r.b = __builtin_amdgcn_raw_buffer_load_b64(rs, voff + 16, 0, 0); }
; DI v32f eseg_unpack(const ESeg& r) { return __builtin_amdgcn_cvt_scalef32_pk32_f32_fp6((v6i){(int)r.a.x, (int)r.a.y, (int)r.a.z, (int)r.a.w, (int)r.b.x, (int)r.b.y}, 1.0f); }
; DI int id_of(const u32x4 (&d)[2], int r, unsigned mask = 0xffffu) { const unsigned w = d[r >> 3][(r >> 1) & 3]; return (r & 1) ? (int)((w >> 16) & mask) : (int)(w & mask); }
;     ...
; #pragma unroll
;         for (int r = 0; r < 16; ++r) {
;             const v32f rr = eseg_unpack(rw[r]); const f32x2 w2 = {wt[r], wt[r]};
; #pragma unroll
;             for (int j = 0; j < 16; ++j) fa[j] = __builtin_elementwise_fma((f32x2){rr[2 * j], rr[2 * j + 1]}, w2, fa[j]);
;             eseg_load(rw[r], VS, id_of(idn, r, mask) * ESEG + s24);
;             if (r & 1) __builtin_amdgcn_sched_barrier(0);
;         }
	v_cvt_scalef32_pk32_f32_fp6 v[0:31], v[56:61], 1.0
	v_mad_u32_u16 v211, v158, 64, v222 op_sel:[1,0,0,0]
	v_mad_u32_u16 v210, v158, s12, v128 op_sel:[1,0,0,0]
	v_pk_fma_f32 v[194:195], v[0:1], v[174:175], v[194:195] op_sel:[0,1,0] op_sel_hi:[1,1,1]
	v_pk_fma_f32 v[196:197], v[2:3], v[174:175], v[196:197] op_sel:[0,1,0] op_sel_hi:[1,1,1]
	v_pk_fma_f32 v[198:199], v[4:5], v[174:175], v[198:199] op_sel:[0,1,0] op_sel_hi:[1,1,1]
	v_pk_fma_f32 v[200:201], v[6:7], v[174:175], v[200:201] op_sel:[0,1,0] op_sel_hi:[1,1,1]
	v_pk_fma_f32 v[202:203], v[8:9], v[174:175], v[202:203] op_sel:[0,1,0] op_sel_hi:[1,1,1]
	v_pk_fma_f32 v[204:205], v[10:11], v[174:175], v[204:205] op_sel:[0,1,0] op_sel_hi:[1,1,1]
	v_pk_fma_f32 v[224:225], v[12:13], v[174:175], v[224:225] op_sel:[0,1,0] op_sel_hi:[1,1,1]
	v_pk_fma_f32 v[226:227], v[14:15], v[174:175], v[226:227] op_sel:[0,1,0] op_sel_hi:[1,1,1]
	v_pk_fma_f32 v[228:229], v[16:17], v[174:175], v[228:229] op_sel:[0,1,0] op_sel_hi:[1,1,1]
	v_pk_fma_f32 v[230:231], v[18:19], v[174:175], v[230:231] op_sel:[0,1,0] op_sel_hi:[1,1,1]
	v_pk_fma_f32 v[232:233], v[20:21], v[174:175], v[232:233] op_sel:[0,1,0] op_sel_hi:[1,1,1]
	v_pk_fma_f32 v[234:235], v[22:23], v[174:175], v[234:235] op_sel:[0,1,0] op_sel_hi:[1,1,1]
	v_pk_fma_f32 v[236:237], v[24:25], v[174:175], v[236:237] op_sel:[0,1,0] op_sel_hi:[1,1,1]
	v_pk_fma_f32 v[182:183], v[26:27], v[174:175], v[182:183] op_sel:[0,1,0] op_sel_hi:[1,1,1]
	v_pk_fma_f32 v[184:185], v[28:29], v[174:175], v[184:185] op_sel:[0,1,0] op_sel_hi:[1,1,1]
	v_pk_fma_f32 v[208:209], v[30:31], v[174:175], v[208:209] op_sel:[0,1,0] op_sel_hi:[1,1,1]
	buffer_load_dwordx4 v[56:59], v210, s[48:51], 0 offen
	buffer_load_dwordx2 v[60:61], v211, s[48:51], 0 offen
	s_waitcnt vmcnt(39)
	v_cvt_scalef32_pk32_f32_fp6 v[0:31], v[92:97], 1.0
	v_mad_u32_u16 v211, v159, 64, v222 op_sel:[0,0,0,0]
	v_mad_u32_u16 v210, v159, s12, v128 op_sel:[0,0,0,0]
	v_pk_fma_f32 v[194:195], v[0:1], v[176:177], v[194:195] op_sel_hi:[1,0,1]
	v_pk_fma_f32 v[196:197], v[2:3], v[176:177], v[196:197] op_sel_hi:[1,0,1]
	v_pk_fma_f32 v[198:199], v[4:5], v[176:177], v[198:199] op_sel_hi:[1,0,1]
	v_pk_fma_f32 v[200:201], v[6:7], v[176:177], v[200:201] op_sel_hi:[1,0,1]
	v_pk_fma_f32 v[202:203], v[8:9], v[176:177], v[202:203] op_sel_hi:[1,0,1]
	v_pk_fma_f32 v[204:205], v[10:11], v[176:177], v[204:205] op_sel_hi:[1,0,1]
	v_pk_fma_f32 v[224:225], v[12:13], v[176:177], v[224:225] op_sel_hi:[1,0,1]
	v_pk_fma_f32 v[226:227], v[14:15], v[176:177], v[226:227] op_sel_hi:[1,0,1]
	v_pk_fma_f32 v[228:229], v[16:17], v[176:177], v[228:229] op_sel_hi:[1,0,1]
	v_pk_fma_f32 v[230:231], v[18:19], v[176:177], v[230:231] op_sel_hi:[1,0,1]
	v_pk_fma_f32 v[232:233], v[20:21], v[176:177], v[232:233] op_sel_hi:[1,0,1]
	v_pk_fma_f32 v[234:235], v[22:23], v[176:177], v[234:235] op_sel_hi:[1,0,1]
	v_pk_fma_f32 v[236:237], v[24:25], v[176:177], v[236:237] op_sel_hi:[1,0,1]
	v_pk_fma_f32 v[182:183], v[26:27], v[176:177], v[182:183] op_sel_hi:[1,0,1]
	v_pk_fma_f32 v[184:185], v[28:29], v[176:177], v[184:185] op_sel_hi:[1,0,1]
	v_pk_fma_f32 v[208:209], v[30:31], v[176:177], v[208:209] op_sel_hi:[1,0,1]
	buffer_load_dwordx4 v[92:95], v210, s[48:51], 0 offen
	buffer_load_dwordx2 v[96:97], v211, s[48:51], 0 offen
	s_waitcnt vmcnt(39)
	v_cvt_scalef32_pk32_f32_fp6 v[0:31], v[62:67], 1.0
	v_mad_u32_u16 v211, v159, 64, v222 op_sel:[1,0,0,0]
	v_mad_u32_u16 v210, v159, s12, v128 op_sel:[1,0,0,0]
	v_pk_fma_f32 v[194:195], v[0:1], v[176:177], v[194:195] op_sel:[0,1,0] op_sel_hi:[1,1,1]
	v_pk_fma_f32 v[196:197], v[2:3], v[176:177], v[196:197] op_sel:[0,1,0] op_sel_hi:[1,1,1]
	v_pk_fma_f32 v[198:199], v[4:5], v[176:177], v[198:199] op_sel:[0,1,0] op_sel_hi:[1,1,1]
	v_pk_fma_f32 v[200:201], v[6:7], v[176:177], v[200:201] op_sel:[0,1,0] op_sel_hi:[1,1,1]
	v_pk_fma_f32 v[202:203], v[8:9], v[176:177], v[202:203] op_sel:[0,1,0] op_sel_hi:[1,1,1]
	v_pk_fma_f32 v[204:205], v[10:11], v[176:177], v[204:205] op_sel:[0,1,0] op_sel_hi:[1,1,1]
	v_pk_fma_f32 v[224:225], v[12:13], v[176:177], v[224:225] op_sel:[0,1,0] op_sel_hi:[1,1,1]
	v_pk_fma_f32 v[226:227], v[14:15], v[176:177], v[226:227] op_sel:[0,1,0] op_sel_hi:[1,1,1]
	v_pk_fma_f32 v[228:229], v[16:17], v[176:177], v[228:229] op_sel:[0,1,0] op_sel_hi:[1,1,1]
	v_pk_fma_f32 v[230:231], v[18:19], v[176:177], v[230:231] op_sel:[0,1,0] op_sel_hi:[1,1,1]
	v_pk_fma_f32 v[232:233], v[20:21], v[176:177], v[232:233] op_sel:[0,1,0] op_sel_hi:[1,1,1]
	v_pk_fma_f32 v[234:235], v[22:23], v[176:177], v[234:235] op_sel:[0,1,0] op_sel_hi:[1,1,1]
	v_pk_fma_f32 v[236:237], v[24:25], v[176:177], v[236:237] op_sel:[0,1,0] op_sel_hi:[1,1,1]
	v_pk_fma_f32 v[182:183], v[26:27], v[176:177], v[182:183] op_sel:[0,1,0] op_sel_hi:[1,1,1]
	v_pk_fma_f32 v[184:185], v[28:29], v[176:177], v[184:185] op_sel:[0,1,0] op_sel_hi:[1,1,1]
	v_pk_fma_f32 v[208:209], v[30:31], v[176:177], v[208:209] op_sel:[0,1,0] op_sel_hi:[1,1,1]
	buffer_load_dwordx4 v[62:65], v210, s[48:51], 0 offen
	buffer_load_dwordx2 v[66:67], v211, s[48:51], 0 offen
	s_waitcnt vmcnt(39)
; DI void eseg_load(ESeg& r, __amdgpu_buffer_rsrc_t rs, int voff) { r.a = __builtin_amdgcn_raw_buffer_load_b128(rs, voff, 0, 0); r.b = __builtin_amdgcn_raw_buffer_load_b64(rs, voff + 16, 0, 0); }
; DI v32f eseg_unpack(const ESeg& r) { return __builtin_amdgcn_cvt_scalef32_pk32_f32_fp6((v6i){(int)r.a.x, (int)r.a.y, (int)r.a.z, (int)r.a.w, (int)r.b.x, (int)r.b.y}, 1.0f); }
; DI int id_of(const u32x4 (&d)[2], int r, unsigned mask = 0xffffu) { const unsigned w = d[r >> 3][(r >> 1) & 3]; return (r & 1) ? (int)((w >> 16) & mask) : (int)(w & mask); }
;     ...
; #pragma unroll
;         for (int r = 0; r < 16; ++r) {
;             const v32f rr = eseg_unpack(rw[r]); const f32x2 w2 = {wt[r], wt[r]};
; #pragma unroll
;             for (int j = 0; j < 16; ++j) fa[j] = __builtin_elementwise_fma((f32x2){rr[2 * j], rr[2 * j + 1]}, w2, fa[j]);
;             eseg_load(rw[r], VS, id_of(idn, r, mask) * ESEG + s24);
;             if (r & 1) __builtin_amdgcn_sched_barrier(0);
;         }
	v_cvt_scalef32_pk32_f32_fp6 v[0:31], v[86:91], 1.0
	v_mad_u32_u16 v211, v160, 64, v222 op_sel:[0,0,0,0]
	v_mad_u32_u16 v210, v160, s12, v128 op_sel:[0,0,0,0]
	v_pk_fma_f32 v[194:195], v[0:1], v[162:163], v[194:195] op_sel_hi:[1,0,1]
	v_pk_fma_f32 v[196:197], v[2:3], v[162:163], v[196:197] op_sel_hi:[1,0,1]
	v_pk_fma_f32 v[198:199], v[4:5], v[162:163], v[198:199] op_sel_hi:[1,0,1]
	v_pk_fma_f32 v[200:201], v[6:7], v[162:163], v[200:201] op_sel_hi:[1,0,1]
	v_pk_fma_f32 v[202:203], v[8:9], v[162:163], v[202:203] op_sel_hi:[1,0,1]
	v_pk_fma_f32 v[204:205], v[10:11], v[162:163], v[204:205] op_sel_hi:[1,0,1]
	v_pk_fma_f32 v[224:225], v[12:13], v[162:163], v[224:225] op_sel_hi:[1,0,1]
	v_pk_fma_f32 v[226:227], v[14:15], v[162:163], v[226:227] op_sel_hi:[1,0,1]
	v_pk_fma_f32 v[228:229], v[16:17], v[162:163], v[228:229] op_sel_hi:[1,0,1]
	v_pk_fma_f32 v[230:231], v[18:19], v[162:163], v[230:231] op_sel_hi:[1,0,1]
	v_pk_fma_f32 v[232:233], v[20:21], v[162:163], v[232:233] op_sel_hi:[1,0,1]
	v_pk_fma_f32 v[234:235], v[22:23], v[162:163], v[234:235] op_sel_hi:[1,0,1]
	v_pk_fma_f32 v[236:237], v[24:25], v[162:163], v[236:237] op_sel_hi:[1,0,1]
	v_pk_fma_f32 v[182:183], v[26:27], v[162:163], v[182:183] op_sel_hi:[1,0,1]
	v_pk_fma_f32 v[184:185], v[28:29], v[162:163], v[184:185] op_sel_hi:[1,0,1]
	v_pk_fma_f32 v[208:209], v[30:31], v[162:163], v[208:209] op_sel_hi:[1,0,1]
	buffer_load_dwordx4 v[86:89], v210, s[48:51], 0 offen
	buffer_load_dwordx2 v[90:91], v211, s[48:51], 0 offen
	s_waitcnt vmcnt(39)
	v_cvt_scalef32_pk32_f32_fp6 v[0:31], v[68:73], 1.0
	v_mad_u32_u16 v211, v160, 64, v222 op_sel:[1,0,0,0]
	v_mad_u32_u16 v210, v160, s12, v128 op_sel:[1,0,0,0]
	v_pk_fma_f32 v[194:195], v[0:1], v[162:163], v[194:195] op_sel:[0,1,0] op_sel_hi:[1,1,1]
	v_pk_fma_f32 v[196:197], v[2:3], v[162:163], v[196:197] op_sel:[0,1,0] op_sel_hi:[1,1,1]
	v_pk_fma_f32 v[198:199], v[4:5], v[162:163], v[198:199] op_sel:[0,1,0] op_sel_hi:[1,1,1]
	v_pk_fma_f32 v[200:201], v[6:7], v[162:163], v[200:201] op_sel:[0,1,0] op_sel_hi:[1,1,1]
	v_pk_fma_f32 v[202:203], v[8:9], v[162:163], v[202:203] op_sel:[0,1,0] op_sel_hi:[1,1,1]
	v_pk_fma_f32 v[204:205], v[10:11], v[162:163], v[204:205] op_sel:[0,1,0] op_sel_hi:[1,1,1]
	v_pk_fma_f32 v[224:225], v[12:13], v[162:163], v[224:225] op_sel:[0,1,0] op_sel_hi:[1,1,1]
	v_pk_fma_f32 v[226:227], v[14:15], v[162:163], v[226:227] op_sel:[0,1,0] op_sel_hi:[1,1,1]
	v_pk_fma_f32 v[228:229], v[16:17], v[162:163], v[228:229] op_sel:[0,1,0] op_sel_hi:[1,1,1]
	v_pk_fma_f32 v[230:231], v[18:19], v[162:163], v[230:231] op_sel:[0,1,0] op_sel_hi:[1,1,1]
	v_pk_fma_f32 v[232:233], v[20:21], v[162:163], v[232:233] op_sel:[0,1,0] op_sel_hi:[1,1,1]
	v_pk_fma_f32 v[234:235], v[22:23], v[162:163], v[234:235] op_sel:[0,1,0] op_sel_hi:[1,1,1]
	v_pk_fma_f32 v[236:237], v[24:25], v[162:163], v[236:237] op_sel:[0,1,0] op_sel_hi:[1,1,1]
	v_pk_fma_f32 v[182:183], v[26:27], v[162:163], v[182:183] op_sel:[0,1,0] op_sel_hi:[1,1,1]
	v_pk_fma_f32 v[184:185], v[28:29], v[162:163], v[184:185] op_sel:[0,1,0] op_sel_hi:[1,1,1]
	v_pk_fma_f32 v[208:209], v[30:31], v[162:163], v[208:209] op_sel:[0,1,0] op_sel_hi:[1,1,1]
	buffer_load_dwordx4 v[68:71], v210, s[48:51], 0 offen
	buffer_load_dwordx2 v[72:73], v211, s[48:51], 0 offen
	s_waitcnt vmcnt(39)
	v_cvt_scalef32_pk32_f32_fp6 v[0:31], v[80:85], 1.0
	v_mad_u32_u16 v211, v161, 64, v222 op_sel:[0,0,0,0]
	v_mad_u32_u16 v210, v161, s12, v128 op_sel:[0,0,0,0]
	v_pk_fma_f32 v[194:195], v[0:1], v[164:165], v[194:195] op_sel_hi:[1,0,1]
	v_pk_fma_f32 v[196:197], v[2:3], v[164:165], v[196:197] op_sel_hi:[1,0,1]
	v_pk_fma_f32 v[198:199], v[4:5], v[164:165], v[198:199] op_sel_hi:[1,0,1]
	v_pk_fma_f32 v[200:201], v[6:7], v[164:165], v[200:201] op_sel_hi:[1,0,1]
	v_pk_fma_f32 v[202:203], v[8:9], v[164:165], v[202:203] op_sel_hi:[1,0,1]
	v_pk_fma_f32 v[204:205], v[10:11], v[164:165], v[204:205] op_sel_hi:[1,0,1]
	v_pk_fma_f32 v[224:225], v[12:13], v[164:165], v[224:225] op_sel_hi:[1,0,1]
	v_pk_fma_f32 v[226:227], v[14:15], v[164:165], v[226:227] op_sel_hi:[1,0,1]
	v_pk_fma_f32 v[228:229], v[16:17], v[164:165], v[228:229] op_sel_hi:[1,0,1]
	v_pk_fma_f32 v[230:231], v[18:19], v[164:165], v[230:231] op_sel_hi:[1,0,1]
	v_pk_fma_f32 v[232:233], v[20:21], v[164:165], v[232:233] op_sel_hi:[1,0,1]
	v_pk_fma_f32 v[234:235], v[22:23], v[164:165], v[234:235] op_sel_hi:[1,0,1]
	v_pk_fma_f32 v[236:237], v[24:25], v[164:165], v[236:237] op_sel_hi:[1,0,1]
	v_pk_fma_f32 v[182:183], v[26:27], v[164:165], v[182:183] op_sel_hi:[1,0,1]
	v_pk_fma_f32 v[184:185], v[28:29], v[164:165], v[184:185] op_sel_hi:[1,0,1]
	v_pk_fma_f32 v[208:209], v[30:31], v[164:165], v[208:209] op_sel_hi:[1,0,1]
	buffer_load_dwordx4 v[80:83], v210, s[48:51], 0 offen
	buffer_load_dwordx2 v[84:85], v211, s[48:51], 0 offen
	s_waitcnt vmcnt(39)
; template <int CTRL> DI float dpp_add(float x) { return x + __uint_as_float(__builtin_amdgcn_update_dpp(0u, __float_as_uint(x), CTRL, 0xf, 0xf, true)); }
; DI void eseg_load(ESeg& r, __amdgpu_buffer_rsrc_t rs, int voff) { r.a = __builtin_amdgcn_raw_buffer_load_b128(rs, voff, 0, 0); r.b = __builtin_amdgcn_raw_buffer_load_b64(rs, voff + 16, 0, 0); }
; DI v32f eseg_unpack(const ESeg& r) { return __builtin_amdgcn_cvt_scalef32_pk32_f32_fp6((v6i){(int)r.a.x, (int)r.a.y, (int)r.a.z, (int)r.a.w, (int)r.b.x, (int)r.b.y}, 1.0f); }
; DI int id_of(const u32x4 (&d)[2], int r, unsigned mask = 0xffffu) { const unsigned w = d[r >> 3][(r >> 1) & 3]; return (r & 1) ? (int)((w >> 16) & mask) : (int)(w & mask); }
;     ...
; #pragma unroll
;         for (int r = 0; r < 16; ++r) {
;             const v32f rr = eseg_unpack(rw[r]); const f32x2 w2 = {wt[r], wt[r]};
; #pragma unroll
;             for (int j = 0; j < 16; ++j) fa[j] = __builtin_elementwise_fma((f32x2){rr[2 * j], rr[2 * j + 1]}, w2, fa[j]);
;             eseg_load(rw[r], VS, id_of(idn, r, mask) * ESEG + s24);
;             if (r & 1) __builtin_amdgcn_sched_barrier(0);
;         }
;         float f16[16], f8[8];
; #pragma unroll
;         for (int j = 0; j < 16; ++j) { const float lo = (j & 1) ? fa[j >> 1].y : fa[j >> 1].x, hi = (j & 1) ? fa[8 + (j >> 1)].y : fa[8 + (j >> 1)].x;
;             const auto a = __builtin_amdgcn_permlane32_swap(__float_as_uint(lo), __float_as_uint(hi), false, false); f16[j] = __uint_as_float(a[0]) + __uint_as_float(a[1]); }
; #pragma unroll
;         for (int j = 0; j < 8; ++j) { const auto a = __builtin_amdgcn_permlane16_swap(__float_as_uint(f16[j]), __float_as_uint(f16[j + 8]), false, false); f8[j] = __uint_as_float(a[0]) + __uint_as_float(a[1]); }
; #pragma unroll
;         for (int j = 0; j < 8; ++j) f8[j] = dpp_add<0x128>(f8[j]);
;         f32x4 z;
;         z.x = ALPHA * x1.x + g2.x * (b3 ? f8[4] : f8[0]); z.y = ALPHA * x1.y + g2.y * (b3 ? f8[5] : f8[1]); z.z = ALPHA * x1.z + g2.z * (b3 ? f8[6] : f8[2]); z.w = ALPHA * x1.w + g2.w * (b3 ? f8[7] : f8[3]);
;         if (!dry) *(f32x4*)xp = z;
;         if (tn >= nrows) break;
;         t = tn; idn[0] = idnn[0]; idn[1] = idnn[1];
	v_cvt_scalef32_pk32_f32_fp6 v[0:31], v[74:79], 1.0
	v_mad_u32_u16 v211, v161, 64, v222 op_sel:[1,0,0,0]
	v_mad_u32_u16 v210, v161, s12, v128 op_sel:[1,0,0,0]
	v_pk_fma_f32 v[194:195], v[0:1], v[164:165], v[194:195] op_sel:[0,1,0] op_sel_hi:[1,1,1]
	v_pk_fma_f32 v[196:197], v[2:3], v[164:165], v[196:197] op_sel:[0,1,0] op_sel_hi:[1,1,1]
	v_pk_fma_f32 v[228:229], v[16:17], v[164:165], v[228:229] op_sel:[0,1,0] op_sel_hi:[1,1,1]
	v_pk_fma_f32 v[16:17], v[20:21], v[164:165], v[232:233] op_sel:[0,1,0] op_sel_hi:[1,1,1]
	v_pk_fma_f32 v[198:199], v[4:5], v[164:165], v[198:199] op_sel:[0,1,0] op_sel_hi:[1,1,1]
	v_pk_fma_f32 v[200:201], v[6:7], v[164:165], v[200:201] op_sel:[0,1,0] op_sel_hi:[1,1,1]
	v_pk_fma_f32 v[202:203], v[8:9], v[164:165], v[202:203] op_sel:[0,1,0] op_sel_hi:[1,1,1]
	v_pk_fma_f32 v[8:9], v[10:11], v[164:165], v[204:205] op_sel:[0,1,0] op_sel_hi:[1,1,1]
	v_pk_fma_f32 v[4:5], v[12:13], v[164:165], v[224:225] op_sel:[0,1,0] op_sel_hi:[1,1,1]
	v_pk_fma_f32 v[0:1], v[14:15], v[164:165], v[226:227] op_sel:[0,1,0] op_sel_hi:[1,1,1]
	v_pk_fma_f32 v[18:19], v[18:19], v[164:165], v[230:231] op_sel:[0,1,0] op_sel_hi:[1,1,1]
	v_pk_fma_f32 v[14:15], v[22:23], v[164:165], v[234:235] op_sel:[0,1,0] op_sel_hi:[1,1,1]
	v_pk_fma_f32 v[12:13], v[24:25], v[164:165], v[236:237] op_sel:[0,1,0] op_sel_hi:[1,1,1]
	v_pk_fma_f32 v[10:11], v[26:27], v[164:165], v[182:183] op_sel:[0,1,0] op_sel_hi:[1,1,1]
	v_pk_fma_f32 v[6:7], v[28:29], v[164:165], v[184:185] op_sel:[0,1,0] op_sel_hi:[1,1,1]
	v_pk_fma_f32 v[2:3], v[30:31], v[164:165], v[208:209] op_sel:[0,1,0] op_sel_hi:[1,1,1]
	buffer_load_dwordx4 v[74:77], v210, s[48:51], 0 offen
	buffer_load_dwordx2 v[78:79], v211, s[48:51], 0 offen
	v_permlane32_swap_b32_e32 v194, v228
	v_permlane32_swap_b32_e32 v195, v229
	v_permlane32_swap_b32_e32 v196, v18
	v_permlane32_swap_b32_e32 v197, v19
	v_permlane32_swap_b32_e32 v198, v16
	v_permlane32_swap_b32_e32 v199, v17
	v_permlane32_swap_b32_e32 v200, v14
	v_permlane32_swap_b32_e32 v201, v15
	v_permlane32_swap_b32_e32 v202, v12
	v_permlane32_swap_b32_e32 v203, v13
	v_permlane32_swap_b32_e32 v8, v10
	v_permlane32_swap_b32_e32 v9, v11
	v_permlane32_swap_b32_e32 v4, v6
	v_permlane32_swap_b32_e32 v5, v7
	v_permlane32_swap_b32_e32 v0, v2
	v_permlane32_swap_b32_e32 v1, v3
	v_add_f32_e32 v20, v194, v228
	v_add_f32_e32 v21, v195, v229
	v_add_f32_e32 v18, v196, v18
	v_add_f32_e32 v19, v197, v19
	v_add_f32_e32 v16, v198, v16
	v_add_f32_e32 v17, v199, v17
	v_add_f32_e32 v14, v200, v14
	v_add_f32_e32 v15, v201, v15
	v_add_f32_e32 v12, v202, v12
	v_add_f32_e32 v13, v203, v13
	v_add_f32_e32 v8, v8, v10
	v_add_f32_e32 v9, v9, v11
	v_add_f32_e32 v4, v4, v6
	v_add_f32_e32 v5, v5, v7
	v_add_f32_e32 v0, v0, v2
	v_add_f32_e32 v1, v1, v3
	v_permlane16_swap_b32_e32 v20, v12
	v_permlane16_swap_b32_e32 v21, v13
	v_permlane16_swap_b32_e32 v18, v8
	v_permlane16_swap_b32_e32 v19, v9
	v_permlane16_swap_b32_e32 v16, v4
	v_permlane16_swap_b32_e32 v17, v5
	v_permlane16_swap_b32_e32 v14, v0
	v_permlane16_swap_b32_e32 v15, v1
	v_pk_add_f32 v[2:3], v[20:21], v[12:13]
	v_pk_add_f32 v[4:5], v[16:17], v[4:5]
	v_pk_add_f32 v[8:9], v[18:19], v[8:9]
	v_pk_add_f32 v[0:1], v[14:15], v[0:1]
	v_mov_b32_dpp v6, v2 row_ror:8 row_mask:0xf bank_mask:0xf bound_ctrl:1
	v_mov_b32_dpp v7, v3 row_ror:8 row_mask:0xf bank_mask:0xf bound_ctrl:1
	v_mov_b32_dpp v10, v4 row_ror:8 row_mask:0xf bank_mask:0xf bound_ctrl:1
	v_mov_b32_dpp v11, v5 row_ror:8 row_mask:0xf bank_mask:0xf bound_ctrl:1
	v_mov_b32_dpp v12, v8 row_ror:8 row_mask:0xf bank_mask:0xf bound_ctrl:1
	v_mov_b32_dpp v13, v9 row_ror:8 row_mask:0xf bank_mask:0xf bound_ctrl:1
	v_mov_b32_dpp v14, v0 row_ror:8 row_mask:0xf bank_mask:0xf bound_ctrl:1
	v_mov_b32_dpp v15, v1 row_ror:8 row_mask:0xf bank_mask:0xf bound_ctrl:1
	v_pk_add_f32 v[8:9], v[8:9], v[12:13]
	v_pk_add_f32 v[2:3], v[2:3], v[6:7]
	v_pk_add_f32 v[4:5], v[4:5], v[10:11]
	v_pk_add_f32 v[0:1], v[0:1], v[14:15]
	v_cndmask_b32_e32 v3, v5, v3, vcc
	v_cndmask_b32_e32 v1, v1, v9, vcc
	v_cndmask_b32_e32 v0, v0, v8, vcc
	v_cndmask_b32_e32 v2, v4, v2, vcc
	s_waitcnt vmcnt(32)
	v_pk_mul_f32 v[0:1], v[172:173], v[0:1]
	v_pk_mul_f32 v[4:5], v[170:171], v[2:3]
	v_mov_b64_e32 v[158:159], v[130:131]
	v_mov_b64_e32 v[160:161], v[132:133]
	v_pk_fma_f32 v[2:3], v[168:169], s[14:15], v[0:1] op_sel_hi:[1,0,1]
	v_pk_fma_f32 v[0:1], v[166:167], s[14:15], v[4:5] op_sel_hi:[1,0,1]
	v_mov_b64_e32 v[186:187], v[134:135]
	v_mov_b64_e32 v[188:189], v[136:137]
	global_store_dwordx4 v[220:221], v[0:3], off
	v_lshl_add_u64 v[220:221], v[220:221], 0, s[8:9]
	s_or_b64 s[10:11], s[36:37], s[10:11]
	v_mov_b64_e32 v[162:163], v[138:139]
	v_mov_b64_e32 v[164:165], v[140:141]
	v_mov_b64_e32 v[174:175], v[142:143]
	v_mov_b64_e32 v[176:177], v[144:145]
	v_mov_b64_e32 v[190:191], v[146:147]
	v_mov_b64_e32 v[192:193], v[148:149]
	v_mov_b64_e32 v[178:179], v[150:151]
	v_mov_b64_e32 v[180:181], v[152:153]
	v_mov_b32_e32 v0, v250
	s_andn2_b64 exec, exec, s[10:11]
	s_cbranch_execnz .LBB0_1095
